# CV once chip-wide; consumer counter loads issued after the P3->P5 arrive atomic instead of before the drain wait
# baseline (speedup 1.0000x reference)
.LBB0_658:
	s_mov_b64 s[4:5], exec
	s_lshl_b32 s2, s68, 8
	v_mbcnt_lo_u32_b32 v1, s4, 0
	s_add_u32 s2, s66, s2
	v_mbcnt_hi_u32_b32 v1, s5, v1
	s_addc_u32 s3, s67, 0
	v_cmp_eq_u32_e32 vcc, 0, v1
	s_and_saveexec_b64 s[6:7], vcc
	s_cbranch_execz .LBB0_660
	s_bcnt1_i32_b64 s4, s[4:5]
	v_mov_b32_e32 v3, 0x1000
	v_mov_b32_e32 v4, s4
	global_atomic_add v3, v3, v4, s[2:3] offset:1024 sc0
	v_readlane_b32 s98, v254, 8
	v_readlane_b32 s99, v254, 9
	v_mov_b32_e32 v18, 0
	s_nop 3
	global_load_dword v20, v18, s[98:99] offset:2176 sc1
	global_load_dword v21, v18, s[98:99] offset:2432 sc1
	global_load_dword v22, v18, s[98:99] offset:2688 sc1
	global_load_dword v23, v18, s[98:99] offset:2944 sc1
	global_load_dword v24, v18, s[98:99] offset:3200 sc1
	global_load_dword v25, v18, s[98:99] offset:3456 sc1
	global_load_dword v26, v18, s[98:99] offset:3712 sc1
	global_load_dword v27, v18, s[98:99] offset:3968 sc1
